# P3 conv tap blocks: bf16 unpack reads the prefetched tap registers directly, 84 of the 96 per-item register copies removed
# speedup vs baseline: 1.0026x; 1.0026x over previous
.LBB0_289:
	s_or_b64 exec, exec, s[4:5]
	v_lshlrev_b32_e32 v1, 4, v77
	v_and_b32_e32 v24, 0x70, v1
	v_lshlrev_b32_e32 v4, 1, v24
	v_ashrrev_i32_e32 v78, 3, v77
	v_lshl_or_b32 v22, s14, 8, v4
	v_add_u32_e32 v25, v0, v78
	s_lshl_b32 s12, s66, 12
	v_lshl_add_u64 v[32:33], s[22:23], 0, v[22:23]
	v_mov_b32_e32 v22, v23
	v_lshl_add_u32 v5, v24, 2, s77
	v_lshl_add_u64 v[34:35], v[32:33], 0, s[40:41]
	v_cmp_lt_i32_e64 s[0:1], 2, v25
	v_add3_u32 v0, v25, s12, -3
	v_mov_b64_e32 v[26:27], v[22:23]
	v_mov_b64_e32 v[18:19], v[22:23]
	v_mov_b64_e32 v[14:15], v[22:23]
	v_mov_b64_e32 v[10:11], v[22:23]
	v_mov_b64_e32 v[16:17], v[22:23]
	v_mov_b64_e32 v[12:13], v[22:23]
	v_mov_b64_e32 v[8:9], v[22:23]
	v_mov_b64_e32 v[6:7], v[22:23]
	v_mov_b32_e32 v89, 0
	v_add_u32_e32 v88, -3, v25
	v_max_i32_e32 v88, 0, v88
	v_add_u32_e32 v88, s12, v88
	v_lshlrev_b64 v[80:81], 13, v[88:89]
	v_lshl_add_u64 v[80:81], v[34:35], 0, v[80:81]
	v_add_u32_e32 v88, -2, v25
	v_max_i32_e32 v88, 0, v88
	v_add_u32_e32 v88, s12, v88
	v_lshlrev_b64 v[82:83], 13, v[88:89]
	v_lshl_add_u64 v[82:83], v[34:35], 0, v[82:83]
	v_add_u32_e32 v88, -1, v25
	v_max_i32_e32 v88, 0, v88
	v_add_u32_e32 v88, s12, v88
	v_lshlrev_b64 v[84:85], 13, v[88:89]
	v_lshl_add_u64 v[84:85], v[34:35], 0, v[84:85]
	v_add_u32_e32 v88, s12, v25
	v_lshlrev_b64 v[86:87], 13, v[88:89]
	v_lshl_add_u64 v[86:87], v[34:35], 0, v[86:87]
	global_load_dwordx4 v[144:147], v[80:81], off
	global_load_dwordx4 v[148:151], v[80:81], off offset:16
	global_load_dwordx4 v[152:155], v[82:83], off
	global_load_dwordx4 v[156:159], v[82:83], off offset:16
	global_load_dwordx4 v[160:163], v[84:85], off
	global_load_dwordx4 v[164:167], v[84:85], off offset:16
	global_load_dwordx4 v[168:171], v[86:87], off
	global_load_dwordx4 v[172:175], v[86:87], off offset:16
	global_load_dwordx4 v[176:179], v[80:81], off offset:1024
	global_load_dwordx4 v[180:183], v[80:81], off offset:1040
	global_load_dwordx4 v[184:187], v[82:83], off offset:1024
	global_load_dwordx4 v[188:191], v[82:83], off offset:1040
	global_load_dwordx4 v[192:195], v[84:85], off offset:1024
	global_load_dwordx4 v[196:199], v[84:85], off offset:1040
	global_load_dwordx4 v[200:203], v[86:87], off offset:1024
	global_load_dwordx4 v[204:207], v[86:87], off offset:1040
	global_load_dwordx4 v[208:211], v[80:81], off offset:2048
	global_load_dwordx4 v[212:215], v[80:81], off offset:2064
	global_load_dwordx4 v[216:219], v[82:83], off offset:2048
	global_load_dwordx4 v[220:223], v[82:83], off offset:2064
	global_load_dwordx4 v[224:227], v[84:85], off offset:2048
	global_load_dwordx4 v[228:231], v[84:85], off offset:2064
	global_load_dwordx4 v[232:235], v[86:87], off offset:2048
	global_load_dwordx4 v[236:239], v[86:87], off offset:2064
	s_and_saveexec_b64 s[4:5], s[0:1]
	s_cbranch_execz .LBB0_291
	v_ashrrev_i32_e32 v1, 31, v0
	v_lshlrev_b64 v[2:3], 13, v[0:1]
	v_lshl_add_u64 v[2:3], v[34:35], 0, v[2:3]
	s_waitcnt vmcnt(22)
	ds_read_b128 v[14:17], v5
	ds_read_b128 v[26:29], v5 offset:16
	ds_read_b128 v[36:39], v5 offset:32
	ds_read_b128 v[40:43], v5 offset:48
	s_nop 0
	v_lshlrev_b32_e32 v2, 16, v144
	v_and_b32_e32 v3, 0xffff0000, v144
	v_lshlrev_b32_e32 v6, 16, v145
	v_and_b32_e32 v7, 0xffff0000, v145
	v_lshlrev_b32_e32 v18, 16, v146
	v_and_b32_e32 v19, 0xffff0000, v146
	v_lshlrev_b32_e32 v8, 16, v147
	v_and_b32_e32 v9, 0xffff0000, v147
	s_nop 0
	v_lshlrev_b32_e32 v30, 16, v148
	v_and_b32_e32 v31, 0xffff0000, v148
	v_lshlrev_b32_e32 v44, 16, v149
	v_and_b32_e32 v45, 0xffff0000, v149
	v_lshlrev_b32_e32 v46, 16, v150
	v_and_b32_e32 v47, 0xffff0000, v150
	v_lshlrev_b32_e32 v48, 16, v151
	v_and_b32_e32 v49, 0xffff0000, v151
	s_waitcnt lgkmcnt(3)
	v_pk_fma_f32 v[10:11], v[14:15], v[2:3], 0 op_sel_hi:[1,1,0]
	v_pk_fma_f32 v[14:15], v[16:17], v[6:7], 0 op_sel_hi:[1,1,0]
	s_waitcnt lgkmcnt(2)
	v_pk_fma_f32 v[6:7], v[26:27], v[18:19], 0 op_sel_hi:[1,1,0]
	v_pk_fma_f32 v[8:9], v[28:29], v[8:9], 0 op_sel_hi:[1,1,0]
	s_waitcnt lgkmcnt(1)
	v_pk_fma_f32 v[18:19], v[36:37], v[30:31], 0 op_sel_hi:[1,1,0]
	v_pk_fma_f32 v[26:27], v[38:39], v[44:45], 0 op_sel_hi:[1,1,0]
	s_waitcnt lgkmcnt(0)
	v_pk_fma_f32 v[12:13], v[40:41], v[46:47], 0 op_sel_hi:[1,1,0]
	v_pk_fma_f32 v[16:17], v[42:43], v[48:49], 0 op_sel_hi:[1,1,0]
.LBB0_291:
	s_or_b64 exec, exec, s[4:5]
	v_cmp_lt_i32_e64 s[4:5], 1, v25
	v_add3_u32 v2, v25, s12, -2
	s_and_saveexec_b64 s[6:7], s[4:5]
	s_cbranch_execz .LBB0_293
	v_ashrrev_i32_e32 v3, 31, v2
	v_lshlrev_b64 v[28:29], 13, v[2:3]
	v_lshl_add_u64 v[36:37], v[34:35], 0, v[28:29]
	s_waitcnt vmcnt(20)
	s_nop 0
	ds_read_b128 v[40:43], v5 offset:512
	ds_read_b128 v[44:47], v5 offset:528
	ds_read_b128 v[48:51], v5 offset:544
	ds_read_b128 v[80:83], v5 offset:560
	s_nop 0
	v_lshlrev_b32_e32 v84, 16, v152
	v_and_b32_e32 v85, 0xffff0000, v152
	v_lshlrev_b32_e32 v28, 16, v153
	v_and_b32_e32 v29, 0xffff0000, v153
	v_lshlrev_b32_e32 v86, 16, v154
	v_and_b32_e32 v87, 0xffff0000, v154
	v_lshlrev_b32_e32 v30, 16, v155
	v_and_b32_e32 v31, 0xffff0000, v155
	s_nop 0
	v_lshlrev_b32_e32 v88, 16, v156
	v_and_b32_e32 v89, 0xffff0000, v156
	v_lshlrev_b32_e32 v36, 16, v157
	v_and_b32_e32 v37, 0xffff0000, v157
	v_lshlrev_b32_e32 v90, 16, v158
	v_and_b32_e32 v91, 0xffff0000, v158
	v_lshlrev_b32_e32 v38, 16, v159
	v_and_b32_e32 v39, 0xffff0000, v159
	s_waitcnt lgkmcnt(3)
	v_pk_fma_f32 v[10:11], v[40:41], v[84:85], v[10:11]
	v_pk_fma_f32 v[14:15], v[42:43], v[28:29], v[14:15]
	s_waitcnt lgkmcnt(2)
	v_pk_fma_f32 v[6:7], v[44:45], v[86:87], v[6:7]
	v_pk_fma_f32 v[8:9], v[46:47], v[30:31], v[8:9]
	s_waitcnt lgkmcnt(1)
	v_pk_fma_f32 v[18:19], v[48:49], v[88:89], v[18:19]
	v_pk_fma_f32 v[26:27], v[50:51], v[36:37], v[26:27]
	s_waitcnt lgkmcnt(0)
	v_pk_fma_f32 v[12:13], v[80:81], v[90:91], v[12:13]
	v_pk_fma_f32 v[16:17], v[82:83], v[38:39], v[16:17]
.LBB0_293:
	s_or_b64 exec, exec, s[6:7]
	v_cmp_lt_i32_e64 s[6:7], 0, v25
	v_add3_u32 v28, v25, s12, -1
	s_and_saveexec_b64 s[8:9], s[6:7]
	s_cbranch_execz .LBB0_295
	v_ashrrev_i32_e32 v29, 31, v28
	v_lshlrev_b64 v[30:31], 13, v[28:29]
	v_lshl_add_u64 v[30:31], v[34:35], 0, v[30:31]
	s_waitcnt vmcnt(18)
	ds_read_b128 v[44:47], v5 offset:1024
	ds_read_b128 v[48:51], v5 offset:1040
	ds_read_b128 v[80:83], v5 offset:1056
	ds_read_b128 v[84:87], v5 offset:1072
	s_nop 0
	v_lshlrev_b32_e32 v30, 16, v160
	v_and_b32_e32 v31, 0xffff0000, v160
	v_lshlrev_b32_e32 v36, 16, v161
	v_and_b32_e32 v37, 0xffff0000, v161
	v_lshlrev_b32_e32 v88, 16, v162
	v_and_b32_e32 v89, 0xffff0000, v162
	v_lshlrev_b32_e32 v38, 16, v163
	v_and_b32_e32 v39, 0xffff0000, v163
	s_nop 0
	v_lshlrev_b32_e32 v90, 16, v164
	v_and_b32_e32 v91, 0xffff0000, v164
	v_lshlrev_b32_e32 v40, 16, v165
	v_and_b32_e32 v41, 0xffff0000, v165
	v_lshlrev_b32_e32 v92, 16, v166
	v_and_b32_e32 v93, 0xffff0000, v166
	v_lshlrev_b32_e32 v42, 16, v167
	v_and_b32_e32 v43, 0xffff0000, v167
	s_waitcnt lgkmcnt(3)
	v_pk_fma_f32 v[10:11], v[44:45], v[30:31], v[10:11]
	v_pk_fma_f32 v[14:15], v[46:47], v[36:37], v[14:15]
	s_waitcnt lgkmcnt(2)
	v_pk_fma_f32 v[6:7], v[48:49], v[88:89], v[6:7]
	v_pk_fma_f32 v[8:9], v[50:51], v[38:39], v[8:9]
	s_waitcnt lgkmcnt(1)
	v_pk_fma_f32 v[18:19], v[80:81], v[90:91], v[18:19]
	v_pk_fma_f32 v[26:27], v[82:83], v[40:41], v[26:27]
	s_waitcnt lgkmcnt(0)
	v_pk_fma_f32 v[12:13], v[84:85], v[92:93], v[12:13]
	v_pk_fma_f32 v[16:17], v[86:87], v[42:43], v[16:17]
.LBB0_295:
	s_or_b64 exec, exec, s[8:9]
	v_add_u32_e32 v30, s12, v25
	v_cmp_lt_i32_e64 s[8:9], -1, v25
	v_ashrrev_i32_e32 v31, 31, v30
	s_and_saveexec_b64 s[12:13], s[8:9]
	s_cbranch_execz .LBB0_297
	v_lshlrev_b64 v[36:37], 13, v[30:31]
	v_lshl_add_u64 v[38:39], v[34:35], 0, v[36:37]
	s_waitcnt vmcnt(16)
	s_nop 0
	ds_read_b128 v[42:45], v5 offset:1536
	ds_read_b128 v[46:49], v5 offset:1552
	ds_read_b128 v[80:83], v5 offset:1568
	ds_read_b128 v[84:87], v5 offset:1584
	s_nop 0
	v_lshlrev_b32_e32 v50, 16, v168
	v_and_b32_e32 v51, 0xffff0000, v168
	v_lshlrev_b32_e32 v34, 16, v169
	v_and_b32_e32 v35, 0xffff0000, v169
	v_lshlrev_b32_e32 v88, 16, v170
	v_and_b32_e32 v89, 0xffff0000, v170
	v_lshlrev_b32_e32 v36, 16, v171
	v_and_b32_e32 v37, 0xffff0000, v171
	s_nop 0
	v_lshlrev_b32_e32 v90, 16, v172
	v_and_b32_e32 v91, 0xffff0000, v172
	v_lshlrev_b32_e32 v38, 16, v173
	v_and_b32_e32 v39, 0xffff0000, v173
	v_lshlrev_b32_e32 v92, 16, v174
	v_and_b32_e32 v93, 0xffff0000, v174
	v_lshlrev_b32_e32 v40, 16, v175
	v_and_b32_e32 v41, 0xffff0000, v175
	s_waitcnt lgkmcnt(3)
	v_pk_fma_f32 v[10:11], v[42:43], v[50:51], v[10:11]
	v_pk_fma_f32 v[14:15], v[44:45], v[34:35], v[14:15]
	s_waitcnt lgkmcnt(2)
	v_pk_fma_f32 v[6:7], v[46:47], v[88:89], v[6:7]
	v_pk_fma_f32 v[8:9], v[48:49], v[36:37], v[8:9]
	s_waitcnt lgkmcnt(1)
	v_pk_fma_f32 v[18:19], v[80:81], v[90:91], v[18:19]
	v_pk_fma_f32 v[26:27], v[82:83], v[38:39], v[26:27]
	s_waitcnt lgkmcnt(0)
	v_pk_fma_f32 v[12:13], v[84:85], v[92:93], v[12:13]
	v_pk_fma_f32 v[16:17], v[86:87], v[40:41], v[16:17]

.LBB0_301:
	v_lshlrev_b64 v[80:81], 13, v[30:31]
	v_lshl_add_u64 v[50:51], v[50:51], 0, v[80:81]
	s_waitcnt vmcnt(8)
	v_mov_b32_e32 v86, v206
	v_mov_b32_e32 v87, v207
	ds_read_b128 v[88:91], v25 offset:1536
	ds_read_b128 v[92:95], v25 offset:1552
	ds_read_b128 v[96:99], v25 offset:1568
	ds_read_b128 v[100:103], v25 offset:1584
	s_nop 0
	v_and_b32_e32 v51, 0xffff0000, v200
	v_lshlrev_b32_e32 v50, 16, v200
	v_and_b32_e32 v105, 0xffff0000, v201
	v_lshlrev_b32_e32 v104, 16, v201
	v_and_b32_e32 v81, 0xffff0000, v202
	v_lshlrev_b32_e32 v80, 16, v202
	v_and_b32_e32 v107, 0xffff0000, v203
	v_lshlrev_b32_e32 v106, 16, v203
	s_nop 0
	v_and_b32_e32 v83, 0xffff0000, v204
	v_lshlrev_b32_e32 v82, 16, v204
	v_and_b32_e32 v109, 0xffff0000, v205
	v_lshlrev_b32_e32 v108, 16, v205
	v_and_b32_e32 v85, 0xffff0000, v206
	v_lshlrev_b32_e32 v84, 16, v206
	v_and_b32_e32 v111, 0xffff0000, v207
	v_lshlrev_b32_e32 v110, 16, v207
	s_waitcnt lgkmcnt(3)
	v_pk_fma_f32 v[34:35], v[88:89], v[50:51], v[34:35]
	v_pk_fma_f32 v[36:37], v[90:91], v[104:105], v[36:37]
	s_waitcnt lgkmcnt(2)
	v_pk_fma_f32 v[38:39], v[92:93], v[80:81], v[38:39]
	v_pk_fma_f32 v[40:41], v[94:95], v[106:107], v[40:41]
	s_waitcnt lgkmcnt(1)
	v_pk_fma_f32 v[42:43], v[96:97], v[82:83], v[42:43]
	v_pk_fma_f32 v[44:45], v[98:99], v[108:109], v[44:45]
	s_waitcnt lgkmcnt(0)
	v_pk_fma_f32 v[46:47], v[100:101], v[84:85], v[46:47]
	v_pk_fma_f32 v[48:49], v[102:103], v[110:111], v[48:49]

.LBB0_306:
	v_lshlrev_b64 v[0:1], 13, v[30:31]
	v_lshl_add_u64 v[28:29], v[48:49], 0, v[0:1]
	s_waitcnt vmcnt(0)
	s_nop 0
	v_mov_b32_e32 v30, v238
	v_mov_b32_e32 v31, v239
	ds_read_b128 v[48:51], v25 offset:1536
	ds_read_b128 v[80:83], v25 offset:1552
	ds_read_b128 v[84:87], v25 offset:1568
	ds_read_b128 v[88:91], v25 offset:1584
	s_nop 0
	v_and_b32_e32 v93, 0xffff0000, v232
	v_lshlrev_b32_e32 v92, 16, v232
	v_and_b32_e32 v95, 0xffff0000, v233
	v_lshlrev_b32_e32 v94, 16, v233
	v_and_b32_e32 v1, 0xffff0000, v234
	v_lshlrev_b32_e32 v0, 16, v234
	v_and_b32_e32 v97, 0xffff0000, v235
	v_lshlrev_b32_e32 v96, 16, v235
	s_nop 0
	v_and_b32_e32 v3, 0xffff0000, v236
	v_lshlrev_b32_e32 v2, 16, v236
	v_and_b32_e32 v99, 0xffff0000, v237
	v_lshlrev_b32_e32 v98, 16, v237
	v_and_b32_e32 v29, 0xffff0000, v238
	v_lshlrev_b32_e32 v28, 16, v238
	v_and_b32_e32 v101, 0xffff0000, v239
	v_lshlrev_b32_e32 v100, 16, v239
	s_waitcnt lgkmcnt(3)
	v_pk_fma_f32 v[46:47], v[48:49], v[92:93], v[46:47]
	v_pk_fma_f32 v[44:45], v[50:51], v[94:95], v[44:45]
	s_waitcnt lgkmcnt(2)
	v_pk_fma_f32 v[42:43], v[80:81], v[0:1], v[42:43]
	v_pk_fma_f32 v[40:41], v[82:83], v[96:97], v[40:41]
	s_waitcnt lgkmcnt(1)
	v_pk_fma_f32 v[38:39], v[84:85], v[2:3], v[38:39]
	v_pk_fma_f32 v[36:37], v[86:87], v[98:99], v[36:37]
	s_waitcnt lgkmcnt(0)
	v_pk_fma_f32 v[32:33], v[88:89], v[28:29], v[32:33]
	v_pk_fma_f32 v[34:35], v[90:91], v[100:101], v[34:35]

.LBB0_343:
	v_ashrrev_i32_e32 v1, 31, v0
	v_lshlrev_b64 v[34:35], 13, v[0:1]
	v_lshl_add_u64 v[38:39], v[50:51], 0, v[34:35]
	s_waitcnt vmcnt(14)
	s_nop 0
	ds_read_b128 v[42:45], v25
	ds_read_b128 v[46:49], v25 offset:16
	ds_read_b128 v[80:83], v25 offset:32
	ds_read_b128 v[84:87], v25 offset:48
	s_nop 0
	v_and_b32_e32 v89, 0xffff0000, v176
	v_lshlrev_b32_e32 v88, 16, v176
	v_and_b32_e32 v91, 0xffff0000, v177
	v_lshlrev_b32_e32 v90, 16, v177
	v_and_b32_e32 v93, 0xffff0000, v178
	v_lshlrev_b32_e32 v92, 16, v178
	v_and_b32_e32 v95, 0xffff0000, v179
	v_lshlrev_b32_e32 v94, 16, v179
	s_nop 0
	v_and_b32_e32 v97, 0xffff0000, v180
	v_lshlrev_b32_e32 v96, 16, v180
	v_and_b32_e32 v99, 0xffff0000, v181
	v_lshlrev_b32_e32 v98, 16, v181
	v_and_b32_e32 v101, 0xffff0000, v182
	v_lshlrev_b32_e32 v100, 16, v182
	v_and_b32_e32 v103, 0xffff0000, v183
	v_lshlrev_b32_e32 v102, 16, v183
	s_waitcnt lgkmcnt(3)
	v_pk_fma_f32 v[34:35], v[42:43], v[88:89], 0 op_sel_hi:[1,1,0]
	v_pk_fma_f32 v[36:37], v[44:45], v[90:91], 0 op_sel_hi:[1,1,0]
	s_waitcnt lgkmcnt(2)
	v_pk_fma_f32 v[38:39], v[46:47], v[92:93], 0 op_sel_hi:[1,1,0]
	v_pk_fma_f32 v[40:41], v[48:49], v[94:95], 0 op_sel_hi:[1,1,0]
	s_waitcnt lgkmcnt(1)
	v_pk_fma_f32 v[42:43], v[80:81], v[96:97], 0 op_sel_hi:[1,1,0]
	v_pk_fma_f32 v[44:45], v[82:83], v[98:99], 0 op_sel_hi:[1,1,0]
	s_waitcnt lgkmcnt(0)
	v_pk_fma_f32 v[46:47], v[84:85], v[100:101], 0 op_sel_hi:[1,1,0]
	v_pk_fma_f32 v[48:49], v[86:87], v[102:103], 0 op_sel_hi:[1,1,0]
	s_or_b64 exec, exec, s[12:13]
	s_and_saveexec_b64 s[12:13], s[4:5]
	s_cbranch_execz .LBB0_299
.LBB0_344:
	v_ashrrev_i32_e32 v3, 31, v2
	v_lshlrev_b64 v[80:81], 13, v[2:3]
	v_lshl_add_u64 v[84:85], v[50:51], 0, v[80:81]
	s_waitcnt vmcnt(12)
	s_nop 0
	v_mov_b32_e32 v86, v190
	v_mov_b32_e32 v87, v191
	ds_read_b128 v[88:91], v25 offset:512
	ds_read_b128 v[92:95], v25 offset:528
	ds_read_b128 v[96:99], v25 offset:544
	ds_read_b128 v[100:103], v25 offset:560
	s_nop 0
	v_and_b32_e32 v105, 0xffff0000, v184
	v_lshlrev_b32_e32 v104, 16, v184
	v_and_b32_e32 v107, 0xffff0000, v185
	v_lshlrev_b32_e32 v106, 16, v185
	v_and_b32_e32 v81, 0xffff0000, v186
	v_lshlrev_b32_e32 v80, 16, v186
	v_and_b32_e32 v109, 0xffff0000, v187
	v_lshlrev_b32_e32 v108, 16, v187
	s_nop 0
	v_and_b32_e32 v83, 0xffff0000, v188
	v_lshlrev_b32_e32 v82, 16, v188
	v_and_b32_e32 v111, 0xffff0000, v189
	v_lshlrev_b32_e32 v110, 16, v189
	v_and_b32_e32 v85, 0xffff0000, v190
	v_lshlrev_b32_e32 v84, 16, v190
	v_and_b32_e32 v113, 0xffff0000, v191
	v_lshlrev_b32_e32 v112, 16, v191
	s_waitcnt lgkmcnt(3)
	v_pk_fma_f32 v[34:35], v[88:89], v[104:105], v[34:35]
	v_pk_fma_f32 v[36:37], v[90:91], v[106:107], v[36:37]
	s_waitcnt lgkmcnt(2)
	v_pk_fma_f32 v[38:39], v[92:93], v[80:81], v[38:39]
	v_pk_fma_f32 v[40:41], v[94:95], v[108:109], v[40:41]
	s_waitcnt lgkmcnt(1)
	v_pk_fma_f32 v[42:43], v[96:97], v[82:83], v[42:43]
	v_pk_fma_f32 v[44:45], v[98:99], v[110:111], v[44:45]
	s_waitcnt lgkmcnt(0)
	v_pk_fma_f32 v[46:47], v[100:101], v[84:85], v[46:47]
	v_pk_fma_f32 v[48:49], v[102:103], v[112:113], v[48:49]
	s_or_b64 exec, exec, s[12:13]
	s_and_saveexec_b64 s[12:13], s[6:7]
	s_cbranch_execz .LBB0_300
.LBB0_345:
	v_ashrrev_i32_e32 v29, 31, v28
	v_lshlrev_b64 v[80:81], 13, v[28:29]
	v_lshl_add_u64 v[84:85], v[50:51], 0, v[80:81]
	s_waitcnt vmcnt(10)
	s_nop 0
	v_mov_b32_e32 v86, v198
	v_mov_b32_e32 v87, v199
	ds_read_b128 v[88:91], v25 offset:1024
	ds_read_b128 v[92:95], v25 offset:1040
	ds_read_b128 v[96:99], v25 offset:1056
	ds_read_b128 v[100:103], v25 offset:1072
	s_nop 0
	v_and_b32_e32 v105, 0xffff0000, v192
	v_lshlrev_b32_e32 v104, 16, v192
	v_and_b32_e32 v107, 0xffff0000, v193
	v_lshlrev_b32_e32 v106, 16, v193
	v_and_b32_e32 v81, 0xffff0000, v194
	v_lshlrev_b32_e32 v80, 16, v194
	v_and_b32_e32 v109, 0xffff0000, v195
	v_lshlrev_b32_e32 v108, 16, v195
	s_nop 0
	v_and_b32_e32 v83, 0xffff0000, v196
	v_lshlrev_b32_e32 v82, 16, v196
	v_and_b32_e32 v111, 0xffff0000, v197
	v_lshlrev_b32_e32 v110, 16, v197
	v_and_b32_e32 v85, 0xffff0000, v198
	v_lshlrev_b32_e32 v84, 16, v198
	v_and_b32_e32 v113, 0xffff0000, v199
	v_lshlrev_b32_e32 v112, 16, v199
	s_waitcnt lgkmcnt(3)
	v_pk_fma_f32 v[34:35], v[88:89], v[104:105], v[34:35]
	v_pk_fma_f32 v[36:37], v[90:91], v[106:107], v[36:37]
	s_waitcnt lgkmcnt(2)
	v_pk_fma_f32 v[38:39], v[92:93], v[80:81], v[38:39]
	v_pk_fma_f32 v[40:41], v[94:95], v[108:109], v[40:41]
	s_waitcnt lgkmcnt(1)
	v_pk_fma_f32 v[42:43], v[96:97], v[82:83], v[42:43]
	v_pk_fma_f32 v[44:45], v[98:99], v[110:111], v[44:45]
	s_waitcnt lgkmcnt(0)
	v_pk_fma_f32 v[46:47], v[100:101], v[84:85], v[46:47]
	v_pk_fma_f32 v[48:49], v[102:103], v[112:113], v[48:49]
	s_or_b64 exec, exec, s[12:13]
	s_and_saveexec_b64 s[12:13], s[8:9]
	s_cbranch_execnz .LBB0_301
	s_branch .LBB0_302
.LBB0_346:
	v_ashrrev_i32_e32 v1, 31, v0
	v_lshlrev_b64 v[0:1], 13, v[0:1]
	v_lshl_add_u64 v[0:1], v[48:49], 0, v[0:1]
	s_waitcnt vmcnt(6)
	ds_read_b128 v[40:43], v25
	ds_read_b128 v[80:83], v25 offset:16
	ds_read_b128 v[84:87], v25 offset:32
	ds_read_b128 v[88:91], v25 offset:48
	s_nop 0
	v_and_b32_e32 v1, 0xffff0000, v208
	v_lshlrev_b32_e32 v0, 16, v208
	v_and_b32_e32 v45, 0xffff0000, v209
	v_lshlrev_b32_e32 v44, 16, v209
	v_and_b32_e32 v33, 0xffff0000, v210
	v_lshlrev_b32_e32 v32, 16, v210
	v_and_b32_e32 v51, 0xffff0000, v211
	v_lshlrev_b32_e32 v50, 16, v211
	s_nop 0
	v_and_b32_e32 v35, 0xffff0000, v212
	v_lshlrev_b32_e32 v34, 16, v212
	v_and_b32_e32 v93, 0xffff0000, v213
	v_lshlrev_b32_e32 v92, 16, v213
	v_and_b32_e32 v95, 0xffff0000, v214
	v_lshlrev_b32_e32 v94, 16, v214
	v_and_b32_e32 v97, 0xffff0000, v215
	v_lshlrev_b32_e32 v96, 16, v215
	s_waitcnt lgkmcnt(3)
	v_pk_fma_f32 v[46:47], v[40:41], v[0:1], 0 op_sel_hi:[1,1,0]
	v_pk_fma_f32 v[44:45], v[42:43], v[44:45], 0 op_sel_hi:[1,1,0]
	s_waitcnt lgkmcnt(2)
	v_pk_fma_f32 v[42:43], v[80:81], v[32:33], 0 op_sel_hi:[1,1,0]
	v_pk_fma_f32 v[40:41], v[82:83], v[50:51], 0 op_sel_hi:[1,1,0]
	s_waitcnt lgkmcnt(1)
	v_pk_fma_f32 v[38:39], v[84:85], v[34:35], 0 op_sel_hi:[1,1,0]
	v_pk_fma_f32 v[36:37], v[86:87], v[92:93], 0 op_sel_hi:[1,1,0]
	s_waitcnt lgkmcnt(0)
	v_pk_fma_f32 v[32:33], v[88:89], v[94:95], 0 op_sel_hi:[1,1,0]
	v_pk_fma_f32 v[34:35], v[90:91], v[96:97], 0 op_sel_hi:[1,1,0]
	s_or_b64 exec, exec, s[12:13]
	s_and_saveexec_b64 s[0:1], s[4:5]
	s_cbranch_execz .LBB0_304
.LBB0_347:
	v_ashrrev_i32_e32 v3, 31, v2
	v_lshlrev_b64 v[0:1], 13, v[2:3]
	v_lshl_add_u64 v[50:51], v[48:49], 0, v[0:1]
	s_waitcnt vmcnt(4)
	v_mov_b32_e32 v82, v222
	v_mov_b32_e32 v83, v223
	ds_read_b128 v[84:87], v25 offset:512
	ds_read_b128 v[88:91], v25 offset:528
	ds_read_b128 v[92:95], v25 offset:544
	ds_read_b128 v[96:99], v25 offset:560
	s_nop 0
	v_and_b32_e32 v51, 0xffff0000, v216
	v_lshlrev_b32_e32 v50, 16, v216
	v_and_b32_e32 v101, 0xffff0000, v217
	v_lshlrev_b32_e32 v100, 16, v217
	v_and_b32_e32 v1, 0xffff0000, v218
	v_lshlrev_b32_e32 v0, 16, v218
	v_and_b32_e32 v103, 0xffff0000, v219
	v_lshlrev_b32_e32 v102, 16, v219
	s_nop 0
	v_and_b32_e32 v3, 0xffff0000, v220
	v_lshlrev_b32_e32 v2, 16, v220
	v_and_b32_e32 v105, 0xffff0000, v221
	v_lshlrev_b32_e32 v104, 16, v221
	v_and_b32_e32 v81, 0xffff0000, v222
	v_lshlrev_b32_e32 v80, 16, v222
	v_and_b32_e32 v107, 0xffff0000, v223
	v_lshlrev_b32_e32 v106, 16, v223
	s_waitcnt lgkmcnt(3)
	v_pk_fma_f32 v[46:47], v[84:85], v[50:51], v[46:47]
	v_pk_fma_f32 v[44:45], v[86:87], v[100:101], v[44:45]
	s_waitcnt lgkmcnt(2)
	v_pk_fma_f32 v[42:43], v[88:89], v[0:1], v[42:43]
	v_pk_fma_f32 v[40:41], v[90:91], v[102:103], v[40:41]
	s_waitcnt lgkmcnt(1)
	v_pk_fma_f32 v[38:39], v[92:93], v[2:3], v[38:39]
	v_pk_fma_f32 v[36:37], v[94:95], v[104:105], v[36:37]
	s_waitcnt lgkmcnt(0)
	v_pk_fma_f32 v[32:33], v[96:97], v[80:81], v[32:33]
	v_pk_fma_f32 v[34:35], v[98:99], v[106:107], v[34:35]
	s_or_b64 exec, exec, s[0:1]
	s_and_saveexec_b64 s[0:1], s[6:7]
	s_cbranch_execz .LBB0_305
.LBB0_348:
	v_ashrrev_i32_e32 v29, 31, v28
	v_lshlrev_b64 v[0:1], 13, v[28:29]
	v_lshl_add_u64 v[28:29], v[48:49], 0, v[0:1]
	s_waitcnt vmcnt(2)
	v_mov_b32_e32 v82, v230
	v_mov_b32_e32 v83, v231
	ds_read_b128 v[84:87], v25 offset:1024
	ds_read_b128 v[88:91], v25 offset:1040
	ds_read_b128 v[92:95], v25 offset:1056
	ds_read_b128 v[96:99], v25 offset:1072
	s_nop 0
	v_and_b32_e32 v29, 0xffff0000, v224
	v_lshlrev_b32_e32 v28, 16, v224
	v_and_b32_e32 v51, 0xffff0000, v225
	v_lshlrev_b32_e32 v50, 16, v225
	v_and_b32_e32 v1, 0xffff0000, v226
	v_lshlrev_b32_e32 v0, 16, v226
	v_and_b32_e32 v101, 0xffff0000, v227
	v_lshlrev_b32_e32 v100, 16, v227
	s_nop 0
	v_and_b32_e32 v3, 0xffff0000, v228
	v_lshlrev_b32_e32 v2, 16, v228
	v_and_b32_e32 v103, 0xffff0000, v229
	v_lshlrev_b32_e32 v102, 16, v229
	v_and_b32_e32 v81, 0xffff0000, v230
	v_lshlrev_b32_e32 v80, 16, v230
	v_and_b32_e32 v105, 0xffff0000, v231
	v_lshlrev_b32_e32 v104, 16, v231
	s_waitcnt lgkmcnt(3)
	v_pk_fma_f32 v[46:47], v[84:85], v[28:29], v[46:47]
	v_pk_fma_f32 v[44:45], v[86:87], v[50:51], v[44:45]
	s_waitcnt lgkmcnt(2)
	v_pk_fma_f32 v[42:43], v[88:89], v[0:1], v[42:43]
	v_pk_fma_f32 v[40:41], v[90:91], v[100:101], v[40:41]
	s_waitcnt lgkmcnt(1)
	v_pk_fma_f32 v[38:39], v[92:93], v[2:3], v[38:39]
	v_pk_fma_f32 v[36:37], v[94:95], v[102:103], v[36:37]
	s_waitcnt lgkmcnt(0)
	v_pk_fma_f32 v[32:33], v[96:97], v[80:81], v[32:33]
	v_pk_fma_f32 v[34:35], v[98:99], v[104:105], v[34:35]
	s_or_b64 exec, exec, s[0:1]
	s_and_saveexec_b64 s[0:1], s[8:9]
	s_cbranch_execnz .LBB0_306
	s_branch .LBB0_307
